# sliding-window loop QK^T: second batch of K-fragment reads issued up front into free quads (on top of the selected-branch V-read hoist)
# speedup vs baseline: 1.0051x; 1.0051x over previous
.LBB0_775:
	s_lshl_b32 s5, s70, 15
	s_add_i32 s75, s5, 0
	v_lshl_add_u32 v2, v163, 1, s75
	v_lshl_add_u32 v0, v164, 1, v2
	ds_read_b128 v[116:119], v0
	ds_read_b128 v[128:131], v0 offset:2048
	v_lshl_add_u32 v2, v165, 1, v2
	ds_read_b128 v[124:127], v2
	ds_read_b128 v[136:139], v2 offset:2048
	ds_read_b128 v[194:197], v0 offset:4096
	ds_read_b128 v[198:201], v0 offset:6144
	ds_read_b128 v[202:205], v2 offset:4096
	ds_read_b128 v[206:209], v2 offset:6144
	s_cmp_eq_u32 s4, s63
	s_waitcnt lgkmcnt(7)
	v_mfma_f32_16x16x32_bf16 v[120:123], v[116:119], v[4:7], v[60:63]
	s_cselect_b64 s[30:31], -1, 0
	s_cmp_eq_u32 s4, s69
	s_cselect_b64 s[4:5], -1, 0
	v_mfma_f32_16x16x32_bf16 v[116:119], v[116:119], v[12:15], v[60:63]
	s_or_b64 s[4:5], s[30:31], s[4:5]
	s_andn2_b64 vcc, exec, s[4:5]
	s_waitcnt lgkmcnt(5)
	v_mfma_f32_16x16x32_bf16 v[132:135], v[124:127], v[8:11], v[120:123]
	v_mfma_f32_16x16x32_bf16 v[124:127], v[124:127], v[16:19], v[116:119]
	v_mfma_f32_16x16x32_bf16 v[116:119], v[128:131], v[4:7], v[60:63]
	s_waitcnt lgkmcnt(4)
	v_mfma_f32_16x16x32_bf16 v[120:123], v[136:139], v[8:11], v[116:119]
	v_mfma_f32_16x16x32_bf16 v[116:119], v[128:131], v[12:15], v[60:63]
	v_mfma_f32_16x16x32_bf16 v[116:119], v[136:139], v[16:19], v[116:119]
	s_waitcnt lgkmcnt(3)
	v_mfma_f32_16x16x32_bf16 v[136:139], v[194:197], v[4:7], v[60:63]
	v_mfma_f32_16x16x32_bf16 v[128:131], v[194:197], v[12:15], v[60:63]
	s_waitcnt lgkmcnt(1)
	v_mfma_f32_16x16x32_bf16 v[136:139], v[202:205], v[8:11], v[136:139]
	v_mfma_f32_16x16x32_bf16 v[128:131], v[202:205], v[16:19], v[128:131]
	v_mfma_f32_16x16x32_bf16 v[140:143], v[198:201], v[4:7], v[60:63]
	v_mfma_f32_16x16x32_bf16 v[144:147], v[198:201], v[12:15], v[60:63]
	s_waitcnt lgkmcnt(0)
	v_mfma_f32_16x16x32_bf16 v[140:143], v[206:209], v[8:11], v[140:143]
	v_mfma_f32_16x16x32_bf16 v[144:147], v[206:209], v[16:19], v[144:147]
	s_cbranch_vccnz .LBB0_777
	v_mov_b32_e32 v3, v166
	v_mov_b32_e32 v174, v176
	s_nop 0
	v_sub_u32_e32 v3, v174, v3
	v_cmp_gt_i32_e64 s[10:11], -16, v3
	s_xor_b64 s[10:11], s[30:31], s[10:11]
	v_cmp_gt_i32_e32 vcc, 0, v3
	v_cndmask_b32_e64 v124, v158, v124, s[10:11]
	v_cmp_gt_i32_e64 s[10:11], -15, v3
	s_xor_b64 s[10:11], s[30:31], s[10:11]
	v_cmp_gt_i32_e64 s[4:5], 1, v3
	v_cndmask_b32_e64 v125, v158, v125, s[10:11]
	v_cmp_gt_i32_e64 s[10:11], -14, v3
	s_xor_b64 s[10:11], s[30:31], s[10:11]
	v_cmp_gt_i32_e64 s[6:7], 2, v3
	v_cndmask_b32_e64 v126, v158, v126, s[10:11]
	v_cmp_gt_i32_e64 s[10:11], -13, v3
	s_xor_b64 s[10:11], s[30:31], s[10:11]
	v_cmp_gt_i32_e64 s[8:9], 3, v3
	v_cndmask_b32_e64 v127, v158, v127, s[10:11]
	v_cmp_gt_i32_e64 s[10:11], 16, v3
	s_xor_b64 s[10:11], s[30:31], s[10:11]
	s_xor_b64 vcc, s[30:31], vcc
	v_cndmask_b32_e64 v120, v158, v120, s[10:11]
	v_cndmask_b32_e64 v128, v158, v128, s[10:11]
	v_cmp_gt_i32_e64 s[10:11], 48, v3
	s_xor_b64 s[10:11], s[30:31], s[10:11]
	s_xor_b64 s[4:5], s[30:31], s[4:5]
	v_cndmask_b32_e64 v140, v158, v140, s[10:11]
	v_cmp_gt_i32_e64 s[10:11], 49, v3
	s_xor_b64 s[10:11], s[30:31], s[10:11]
	s_xor_b64 s[6:7], s[30:31], s[6:7]
	v_cndmask_b32_e64 v141, v158, v141, s[10:11]
	v_cmp_gt_i32_e64 s[10:11], 50, v3
	s_xor_b64 s[8:9], s[30:31], s[8:9]
	s_xor_b64 s[10:11], s[30:31], s[10:11]
	v_cndmask_b32_e32 v132, v158, v132, vcc
	v_cndmask_b32_e64 v133, v158, v133, s[4:5]
	v_cndmask_b32_e64 v134, v158, v134, s[6:7]
	v_cndmask_b32_e64 v135, v158, v135, s[8:9]
	v_cmp_gt_i32_e64 s[12:13], 17, v3
	v_cmp_gt_i32_e64 s[14:15], 18, v3
	v_cmp_gt_i32_e64 s[16:17], 19, v3
	v_cndmask_b32_e32 v116, v158, v116, vcc
	v_cndmask_b32_e64 v117, v158, v117, s[4:5]
	v_cndmask_b32_e64 v118, v158, v118, s[6:7]
	v_cndmask_b32_e64 v119, v158, v119, s[8:9]
	v_cmp_gt_i32_e32 vcc, 32, v3
	v_cmp_gt_i32_e64 s[4:5], 33, v3
	v_cmp_gt_i32_e64 s[6:7], 34, v3
	v_cmp_gt_i32_e64 s[8:9], 35, v3
	v_cndmask_b32_e64 v142, v158, v142, s[10:11]
	v_cmp_gt_i32_e64 s[10:11], 51, v3
	s_xor_b64 s[12:13], s[30:31], s[12:13]
	s_xor_b64 s[14:15], s[30:31], s[14:15]
	s_xor_b64 s[16:17], s[30:31], s[16:17]
	s_xor_b64 vcc, s[30:31], vcc
	s_xor_b64 s[4:5], s[30:31], s[4:5]
	s_xor_b64 s[6:7], s[30:31], s[6:7]
	s_xor_b64 s[8:9], s[30:31], s[8:9]
	s_xor_b64 s[10:11], s[30:31], s[10:11]
	v_cndmask_b32_e64 v121, v158, v121, s[12:13]
	v_cndmask_b32_e64 v122, v158, v122, s[14:15]
	v_cndmask_b32_e64 v123, v158, v123, s[16:17]
	v_cndmask_b32_e32 v136, v158, v136, vcc
	v_cndmask_b32_e64 v137, v158, v137, s[4:5]
	v_cndmask_b32_e64 v138, v158, v138, s[6:7]
	v_cndmask_b32_e64 v139, v158, v139, s[8:9]
	v_cndmask_b32_e64 v129, v158, v129, s[12:13]
	v_cndmask_b32_e64 v130, v158, v130, s[14:15]
	v_cndmask_b32_e64 v131, v158, v131, s[16:17]
	v_cndmask_b32_e64 v143, v158, v143, s[10:11]
	v_cndmask_b32_e32 v144, v158, v144, vcc
	v_cndmask_b32_e64 v145, v158, v145, s[4:5]
	v_cndmask_b32_e64 v146, v158, v146, s[6:7]
	v_cndmask_b32_e64 v147, v158, v147, s[8:9]
.LBB0_777:
	s_cmp_gt_i32 s76, -1
	s_cselect_b64 s[30:31], -1, 0
	s_cmp_lt_i32 s76, 0
	s_cbranch_scc1 .LBB0_780
	ds_read_b128 v[80:83], v0 offset:16384
	ds_read_b128 v[92:95], v0 offset:18432
	ds_read_b128 v[88:91], v2 offset:16384
	ds_read_b128 v[100:103], v2 offset:18432
	ds_read_b128 v[210:213], v0 offset:20480
	ds_read_b128 v[214:217], v0 offset:22528
	ds_read_b128 v[218:221], v2 offset:20480
	ds_read_b128 v[222:225], v2 offset:22528
	s_cmp_eq_u32 s76, s63
	s_cselect_b64 s[34:35], -1, 0
	s_waitcnt lgkmcnt(7)
	v_mfma_f32_16x16x32_bf16 v[84:87], v[80:83], v[4:7], v[60:63]
	s_cmp_eq_u32 s76, s69
	s_cselect_b64 s[4:5], -1, 0
	s_or_b64 s[4:5], s[34:35], s[4:5]
	v_mfma_f32_16x16x32_bf16 v[80:83], v[80:83], v[12:15], v[60:63]
	s_andn2_b64 vcc, exec, s[4:5]
	s_waitcnt lgkmcnt(5)
	v_mfma_f32_16x16x32_bf16 v[96:99], v[88:91], v[8:11], v[84:87]
	v_mfma_f32_16x16x32_bf16 v[88:91], v[88:91], v[16:19], v[80:83]
	v_mfma_f32_16x16x32_bf16 v[80:83], v[92:95], v[4:7], v[60:63]
	s_waitcnt lgkmcnt(4)
	v_mfma_f32_16x16x32_bf16 v[84:87], v[100:103], v[8:11], v[80:83]
	v_mfma_f32_16x16x32_bf16 v[80:83], v[92:95], v[12:15], v[60:63]
	v_mfma_f32_16x16x32_bf16 v[80:83], v[100:103], v[16:19], v[80:83]
	s_waitcnt lgkmcnt(3)
	v_mfma_f32_16x16x32_bf16 v[100:103], v[210:213], v[4:7], v[60:63]
	v_mfma_f32_16x16x32_bf16 v[92:95], v[210:213], v[12:15], v[60:63]
	s_waitcnt lgkmcnt(1)
	v_mfma_f32_16x16x32_bf16 v[100:103], v[218:221], v[8:11], v[100:103]
	v_mfma_f32_16x16x32_bf16 v[92:95], v[218:221], v[16:19], v[92:95]
	v_mfma_f32_16x16x32_bf16 v[104:107], v[214:217], v[4:7], v[60:63]
	v_mfma_f32_16x16x32_bf16 v[108:111], v[214:217], v[12:15], v[60:63]
	s_waitcnt lgkmcnt(0)
	v_mfma_f32_16x16x32_bf16 v[104:107], v[222:225], v[8:11], v[104:107]
	v_mfma_f32_16x16x32_bf16 v[108:111], v[222:225], v[16:19], v[108:111]
	s_cbranch_vccnz .LBB0_780
	v_mov_b32_e32 v0, v166
	v_mov_b32_e32 v2, v176
	s_nop 0
	v_sub_u32_e32 v0, v2, v0
	v_cmp_gt_i32_e64 s[10:11], -16, v0
	s_xor_b64 s[10:11], s[34:35], s[10:11]
	v_cmp_gt_i32_e32 vcc, 0, v0
	v_cndmask_b32_e64 v88, v158, v88, s[10:11]
	v_cmp_gt_i32_e64 s[10:11], -15, v0
	s_xor_b64 s[10:11], s[34:35], s[10:11]
	v_cmp_gt_i32_e64 s[4:5], 1, v0
	v_cndmask_b32_e64 v89, v158, v89, s[10:11]
	v_cmp_gt_i32_e64 s[10:11], -14, v0
	s_xor_b64 s[10:11], s[34:35], s[10:11]
	v_cmp_gt_i32_e64 s[6:7], 2, v0
	v_cndmask_b32_e64 v90, v158, v90, s[10:11]
	v_cmp_gt_i32_e64 s[10:11], -13, v0
	s_xor_b64 s[10:11], s[34:35], s[10:11]
	v_cmp_gt_i32_e64 s[8:9], 3, v0
	v_cndmask_b32_e64 v91, v158, v91, s[10:11]
	v_cmp_gt_i32_e64 s[10:11], 16, v0
	s_xor_b64 s[10:11], s[34:35], s[10:11]
	s_xor_b64 vcc, s[34:35], vcc
	v_cndmask_b32_e64 v84, v158, v84, s[10:11]
	v_cndmask_b32_e64 v92, v158, v92, s[10:11]
	v_cmp_gt_i32_e64 s[10:11], 48, v0
	s_xor_b64 s[10:11], s[34:35], s[10:11]
	s_xor_b64 s[4:5], s[34:35], s[4:5]
	v_cndmask_b32_e64 v104, v158, v104, s[10:11]
	v_cmp_gt_i32_e64 s[10:11], 49, v0
	s_xor_b64 s[10:11], s[34:35], s[10:11]
	s_xor_b64 s[6:7], s[34:35], s[6:7]
	v_cndmask_b32_e64 v105, v158, v105, s[10:11]
	v_cmp_gt_i32_e64 s[10:11], 50, v0
	s_xor_b64 s[8:9], s[34:35], s[8:9]
	s_xor_b64 s[10:11], s[34:35], s[10:11]
	v_cndmask_b32_e32 v96, v158, v96, vcc
	v_cndmask_b32_e64 v97, v158, v97, s[4:5]
	v_cndmask_b32_e64 v98, v158, v98, s[6:7]
	v_cndmask_b32_e64 v99, v158, v99, s[8:9]
	v_cmp_gt_i32_e64 s[12:13], 17, v0
	v_cmp_gt_i32_e64 s[14:15], 18, v0
	v_cmp_gt_i32_e64 s[16:17], 19, v0
	v_cndmask_b32_e32 v80, v158, v80, vcc
	v_cndmask_b32_e64 v81, v158, v81, s[4:5]
	v_cndmask_b32_e64 v82, v158, v82, s[6:7]
	v_cndmask_b32_e64 v83, v158, v83, s[8:9]
	v_cmp_gt_i32_e32 vcc, 32, v0
	v_cmp_gt_i32_e64 s[4:5], 33, v0
	v_cmp_gt_i32_e64 s[6:7], 34, v0
	v_cmp_gt_i32_e64 s[8:9], 35, v0
	v_cndmask_b32_e64 v106, v158, v106, s[10:11]
	v_cmp_gt_i32_e64 s[10:11], 51, v0
	s_xor_b64 s[12:13], s[34:35], s[12:13]
	s_xor_b64 s[14:15], s[34:35], s[14:15]
	s_xor_b64 s[16:17], s[34:35], s[16:17]
	s_xor_b64 vcc, s[34:35], vcc
	s_xor_b64 s[4:5], s[34:35], s[4:5]
	s_xor_b64 s[6:7], s[34:35], s[6:7]
	s_xor_b64 s[8:9], s[34:35], s[8:9]
	s_xor_b64 s[10:11], s[34:35], s[10:11]
	v_cndmask_b32_e64 v85, v158, v85, s[12:13]
	v_cndmask_b32_e64 v86, v158, v86, s[14:15]
	v_cndmask_b32_e64 v87, v158, v87, s[16:17]
	v_cndmask_b32_e32 v100, v158, v100, vcc
	v_cndmask_b32_e64 v101, v158, v101, s[4:5]
	v_cndmask_b32_e64 v102, v158, v102, s[6:7]
	v_cndmask_b32_e64 v103, v158, v103, s[8:9]
	v_cndmask_b32_e64 v93, v158, v93, s[12:13]
	v_cndmask_b32_e64 v94, v158, v94, s[14:15]
	v_cndmask_b32_e64 v95, v158, v95, s[16:17]
	v_cndmask_b32_e64 v107, v158, v107, s[10:11]
	v_cndmask_b32_e32 v108, v158, v108, vcc
	v_cndmask_b32_e64 v109, v158, v109, s[4:5]
	v_cndmask_b32_e64 v110, v158, v110, s[6:7]
	v_cndmask_b32_e64 v111, v158, v111, s[8:9]
